# dilated-attention QK: double-buffered K-fragment LDS reads
# speedup vs baseline: 1.0264x; 1.0007x over previous
; __device__ __forceinline__ void finishSM(f32x16& p0, f32x16& p1, float alpha, float& l_reg, bf16x8& pa0, bf16x8& pa1, bf16x8& pa2, bf16x8& pa3) {
; #pragma unroll
;   for (int r = 0; r < 16; ++r) p1[r] = __builtin_amdgcn_exp2f(p1[r]);
; template <class CF> __device__ __forceinline__ void qkt(f32x16& p0, f32x16& p1, const char* Ks, const bf16x8* qr, const char* qx, int r32, int hi) {
;   p0 = f32x16{}; p1 = f32x16{};
; #pragma unroll
;   for (int d0 = 0; d0 < CF::ND0; ++d0) { const int cb = (d0 * 16 + hi * 8) * 2;
;     bf16x8 b0 = *reinterpret_cast<const bf16x8*>(Ks + (r32) * CF::KPITCH + (cb ^ ((r32 & CF::KSWM) << 4)));
;     bf16x8 b1 = *reinterpret_cast<const bf16x8*>(Ks + (32 + r32) * CF::KPITCH + (cb ^ ((r32 & CF::KSWM) << 4)));
;     bf16x8 q; if (d0 < CF::NQR) q = qr[d0 < CF::NQR ? d0 : 0]; else q = *reinterpret_cast<const bf16x8*>(qx + (d0 - CF::NQR) * 1024);
;     p0 = __builtin_amdgcn_mfma_f32_32x32x16_bf16(b0, q, p0, 0, 0, 0);
;     p1 = __builtin_amdgcn_mfma_f32_32x32x16_bf16(b1, q, p1, 0, 0, 0); }
; }
; __device__ __forceinline__ void bandmask(f32x16& p0, f32x16& p1, int kb, int qi, int hi) {
;   const float ninf = -__builtin_inff();
;   int dq = kb - qi + 4 * hi + 64; asm volatile("" : "+v"(dq));
; #pragma unroll
;   for (int r = 0; r < 16; ++r) { const int c = (r & 3) + 8 * (r >> 2); if ((unsigned)(dq + c) > 128u) p0[r] = ninf; if ((unsigned)(dq + c + 32) > 128u) p1[r] = ninf; }
; }
.LBB0_433:
	ds_read_b128 v[80:83], v195 offset:49152
	ds_read_b128 v[84:87], v195 offset:57344
	ds_read_b128 v[206:209], v197 offset:49152
	ds_read_b128 v[210:213], v197 offset:57344
	s_waitcnt lgkmcnt(3)
	v_mfma_f32_32x32x16_bf16 v[96:111], v[80:83], v[140:143], 0
	s_waitcnt lgkmcnt(2)
	v_mfma_f32_32x32x16_bf16 v[80:95], v[84:87], v[140:143], 0
	ds_read_b128 v[228:231], v196 offset:49152
	ds_read_b128 v[232:235], v196 offset:57344
	s_waitcnt lgkmcnt(3)
	v_mfma_f32_32x32x16_bf16 v[96:111], v[206:209], v[136:139], v[96:111]
	s_waitcnt lgkmcnt(2)
	v_mfma_f32_32x32x16_bf16 v[80:95], v[210:213], v[136:139], v[80:95]
	ds_read_b128 v[206:209], v198 offset:49152
	ds_read_b128 v[210:213], v198 offset:57344
	s_waitcnt lgkmcnt(3)
	v_mfma_f32_32x32x16_bf16 v[96:111], v[228:231], v[132:135], v[96:111]
	s_waitcnt lgkmcnt(2)
	v_mfma_f32_32x32x16_bf16 v[80:95], v[232:235], v[132:135], v[80:95]
	ds_read_b128 v[228:231], v199 offset:49152
	ds_read_b128 v[232:235], v199 offset:57344
	s_waitcnt lgkmcnt(3)
	v_mfma_f32_32x32x16_bf16 v[96:111], v[206:209], v[128:131], v[96:111]
	s_waitcnt lgkmcnt(2)
	v_mfma_f32_32x32x16_bf16 v[80:95], v[210:213], v[128:131], v[80:95]
	ds_read_b128 v[206:209], v201 offset:49152
	ds_read_b128 v[210:213], v201 offset:57344
	s_waitcnt lgkmcnt(3)
	v_mfma_f32_32x32x16_bf16 v[96:111], v[228:231], v[124:127], v[96:111]
	s_waitcnt lgkmcnt(2)
	v_mfma_f32_32x32x16_bf16 v[80:95], v[232:235], v[124:127], v[80:95]
	ds_read_b128 v[228:231], v202 offset:49152
	ds_read_b128 v[232:235], v202 offset:57344
	s_waitcnt lgkmcnt(3)
	v_mfma_f32_32x32x16_bf16 v[96:111], v[206:209], v[120:123], v[96:111]
	s_waitcnt lgkmcnt(2)
	v_mfma_f32_32x32x16_bf16 v[80:95], v[210:213], v[120:123], v[80:95]
	ds_read_b128 v[206:209], v203 offset:49152
	ds_read_b128 v[210:213], v203 offset:57344
	s_waitcnt lgkmcnt(3)
	v_mfma_f32_32x32x16_bf16 v[96:111], v[228:231], v[116:119], v[96:111]
	s_waitcnt lgkmcnt(2)
	v_mfma_f32_32x32x16_bf16 v[80:95], v[232:235], v[116:119], v[80:95]
	s_waitcnt lgkmcnt(1)
	v_mfma_f32_32x32x16_bf16 v[96:111], v[206:209], v[112:115], v[96:111]
	v_subrev_u32_e32 v206, 64, v224
	s_nop 0
	v_cmp_gt_u32_e32 vcc, s91, v206
	s_waitcnt lgkmcnt(0)
	v_mfma_f32_32x32x16_bf16 v[80:95], v[210:213], v[112:115], v[80:95]
	s_nop 6
	v_cndmask_b32_e32 v229, v248, v96, vcc
	v_add_u32_e32 v96, 0xffffff9f, v206
	v_cmp_lt_u32_e32 vcc, s90, v96
	v_exp_f32_e32 v96, v167
	s_nop 0
	v_cndmask_b32_e32 v225, v248, v80, vcc
	v_add_u32_e32 v80, 0xffffff80, v206
	v_cmp_lt_u32_e32 vcc, s90, v80
	v_add_u32_e32 v80, 0xffffffa0, v206
	s_nop 0
	v_cndmask_b32_e32 v230, v248, v97, vcc
	v_cmp_lt_u32_e32 vcc, s90, v80
	v_add_u32_e32 v80, 0xffffff81, v206
	v_exp_f32_e32 v97, v164
	v_cndmask_b32_e32 v228, v248, v81, vcc
	v_cmp_lt_u32_e32 vcc, s90, v80
	v_add_u32_e32 v80, 0xffffffa1, v206
	s_nop 0
	v_cndmask_b32_e32 v231, v248, v98, vcc
	v_cmp_lt_u32_e32 vcc, s90, v80
	v_add_u32_e32 v80, 0xffffff82, v206
	v_exp_f32_e32 v98, v165
	v_cndmask_b32_e32 v82, v248, v82, vcc
	v_cmp_lt_u32_e32 vcc, s90, v80
	v_add_u32_e32 v80, 0xffffffa2, v206
	s_nop 0
	v_cndmask_b32_e32 v232, v248, v99, vcc
	v_cmp_lt_u32_e32 vcc, s90, v80
	v_add_u32_e32 v80, 0xffffff87, v206
	v_exp_f32_e32 v99, v162
	v_cndmask_b32_e32 v83, v248, v83, vcc
	v_cmp_lt_u32_e32 vcc, s90, v80
	v_add_u32_e32 v80, 0xffffffa7, v206
	s_nop 0
	v_cndmask_b32_e32 v233, v248, v100, vcc
	v_cmp_lt_u32_e32 vcc, s90, v80
	v_add_u32_e32 v80, 0xffffff88, v206
	v_exp_f32_e32 v100, v163
	v_cndmask_b32_e32 v84, v248, v84, vcc
	v_cmp_lt_u32_e32 vcc, s90, v80
	v_add_u32_e32 v80, 0xffffffa8, v206
	s_nop 0
	v_cndmask_b32_e32 v234, v248, v101, vcc
	v_cmp_lt_u32_e32 vcc, s90, v80
	v_add_u32_e32 v80, 0xffffff89, v206
	v_exp_f32_e32 v101, v160
	v_cndmask_b32_e32 v85, v248, v85, vcc
	v_cmp_lt_u32_e32 vcc, s90, v80
	v_add_u32_e32 v80, 0xffffffa9, v206
	s_nop 0
	v_cndmask_b32_e32 v235, v248, v102, vcc
	v_cmp_lt_u32_e32 vcc, s90, v80
	v_add_u32_e32 v80, 0xffffff8a, v206
	v_exp_f32_e32 v102, v161
	v_cndmask_b32_e32 v86, v248, v86, vcc
	v_cmp_lt_u32_e32 vcc, s90, v80
	v_add_u32_e32 v80, 0xffffffaa, v206
	s_nop 0
	v_cndmask_b32_e32 v236, v248, v103, vcc
	v_cmp_lt_u32_e32 vcc, s90, v80
	v_add_u32_e32 v80, 0xffffff8f, v206
	v_exp_f32_e32 v103, v174
	v_cndmask_b32_e32 v87, v248, v87, vcc
	v_cmp_lt_u32_e32 vcc, s90, v80
	v_add_u32_e32 v80, 0xffffffaf, v206
	s_nop 0
	v_cndmask_b32_e32 v238, v248, v104, vcc
	v_cmp_lt_u32_e32 vcc, s90, v80
	v_add_u32_e32 v80, 0xffffff90, v206
	v_exp_f32_e32 v104, v175
	v_cndmask_b32_e32 v88, v248, v88, vcc
	v_cmp_lt_u32_e32 vcc, s90, v80
	v_add_u32_e32 v80, 0xffffffb0, v206
	s_nop 0
	v_cndmask_b32_e32 v240, v248, v105, vcc
	v_cmp_lt_u32_e32 vcc, s90, v80
	v_add_u32_e32 v80, 0xffffff91, v206
	v_exp_f32_e32 v105, v172
	v_cndmask_b32_e32 v89, v248, v89, vcc
	v_cmp_lt_u32_e32 vcc, s90, v80
	v_add_u32_e32 v80, 0xffffffb1, v206
	s_nop 0
	v_cndmask_b32_e32 v242, v248, v106, vcc
	v_cmp_lt_u32_e32 vcc, s90, v80
	v_add_u32_e32 v80, 0xffffff92, v206
	v_exp_f32_e32 v106, v173
	v_cndmask_b32_e32 v237, v248, v90, vcc
	v_cmp_lt_u32_e32 vcc, s90, v80
	v_add_u32_e32 v80, 0xffffffb2, v206
	s_nop 0
	v_cndmask_b32_e32 v243, v248, v107, vcc
	v_cmp_lt_u32_e32 vcc, s90, v80
	v_add_u32_e32 v80, 0xffffff97, v206
	v_exp_f32_e32 v107, v170
	v_cndmask_b32_e32 v239, v248, v91, vcc
	v_cmp_lt_u32_e32 vcc, s90, v80
	v_add_u32_e32 v80, 0xffffffb7, v206
	s_nop 0
	v_cndmask_b32_e32 v244, v248, v108, vcc
	v_cmp_lt_u32_e32 vcc, s90, v80
	v_add_u32_e32 v80, 0xffffff98, v206
	v_exp_f32_e32 v108, v171
	v_cndmask_b32_e32 v241, v248, v92, vcc
	v_cmp_lt_u32_e32 vcc, s90, v80
	v_add_u32_e32 v80, 0xffffffb8, v206
	s_nop 0
	v_cndmask_b32_e32 v245, v248, v109, vcc
	v_cmp_lt_u32_e32 vcc, s90, v80
; #define ATT_SBAR() __builtin_amdgcn_sched_barrier(0)
; __device__ __forceinline__ void finishSM(f32x16& p0, f32x16& p1, float alpha, float& l_reg, bf16x8& pa0, bf16x8& pa1, bf16x8& pa2, bf16x8& pa3) {
; #pragma unroll
;   for (int r = 0; r < 16; ++r) p1[r] = __builtin_amdgcn_exp2f(p1[r]);
;   float ps = 0;
; #pragma unroll
;   for (int r = 0; r < 16; ++r) ps += p0[r];
; #pragma unroll
;   for (int r = 0; r < 16; ++r) ps += p1[r];
;   { auto rr = __builtin_amdgcn_permlane32_swap(__float_as_uint(ps), __float_as_uint(ps), false, false);
;     ps = __uint_as_float(rr[0]) + __uint_as_float(rr[1]); }
;   l_reg = l_reg * alpha + ps;
;     ...
;   ATT_PK4(p0, 0, pa0); ATT_PK4(p0, 8, pa1); ATT_PK4(p1, 0, pa2); ATT_PK4(p1, 8, pa3);
; template <int OFF> __device__ __forceinline__ s16x4 tr_read(int vb) {
;   s16x4 r; asm volatile("ds_read_b64_tr_b16 %0, %1 offset:%2" : "=&v"(r) : "v"(vb), "i"(OFF) : "memory"); return r;
; }
; template <int D0> __device__ __forceinline__ void pv_one(f32x16& od, int vb, bf16x8 pa0, bf16x8 pa1, bf16x8 pa2, bf16x8 pa3) {
;   const s16x4 l0 = tr_read<v_rd_off(D0, 0, 0)>(vb), h0 = tr_read<v_rd_off(D0, 0, 1)>(vb), l1 = tr_read<v_rd_off(D0, 1, 0)>(vb), h1 = tr_read<v_rd_off(D0, 1, 1)>(vb);
;   const s16x4 l2 = tr_read<v_rd_off(D0, 2, 0)>(vb), h2 = tr_read<v_rd_off(D0, 2, 1)>(vb), l3 = tr_read<v_rd_off(D0, 3, 0)>(vb), h3 = tr_read<v_rd_off(D0, 3, 1)>(vb);
;   asm volatile("s_waitcnt lgkmcnt(0)" ::: "memory"); ATT_SBAR();
;     ...
;   od = __builtin_amdgcn_mfma_f32_32x32x16_bf16(pa0, ATT_PK(l0, h0), od, 0, 0, 0);
;   od = __builtin_amdgcn_mfma_f32_32x32x16_bf16(pa1, ATT_PK(l1, h1), od, 0, 0, 0);
;   od = __builtin_amdgcn_mfma_f32_32x32x16_bf16(pa2, ATT_PK(l2, h2), od, 0, 0, 0);
;   od = __builtin_amdgcn_mfma_f32_32x32x16_bf16(pa3, ATT_PK(l3, h3), od, 0, 0, 0);
;     ...
; }
; __device__ __forceinline__ void pv_d0(f32x16* o, int vb, bf16x8 pa0, bf16x8 pa1, bf16x8 pa2, bf16x8 pa3) {
;   pv_one<0>(o[0], vb, pa0, pa1, pa2, pa3); pv_one<1>(o[1], vb, pa0, pa1, pa2, pa3); pv_one<2>(o[2], vb, pa0, pa1, pa2, pa3); pv_one<3>(o[3], vb, pa0, pa1, pa2, pa3);
	v_add_u32_e32 v80, 0xffffff99, v206
	v_exp_f32_e32 v109, v168
	v_cndmask_b32_e32 v90, v248, v93, vcc
	v_cmp_lt_u32_e32 vcc, s90, v80
	v_add_u32_e32 v80, 0xffffffb9, v206
	s_nop 0
	v_cndmask_b32_e32 v93, v248, v110, vcc
	v_cmp_lt_u32_e32 vcc, s90, v80
	v_add_u32_e32 v80, 0xffffff9a, v206
	v_exp_f32_e32 v110, v169
	v_cndmask_b32_e32 v91, v248, v94, vcc
	v_cmp_lt_u32_e32 vcc, s90, v80
	v_add_u32_e32 v80, 0xffffffba, v206
	s_nop 0
	v_cndmask_b32_e32 v94, v248, v111, vcc
	v_cmp_lt_u32_e32 vcc, s90, v80
	v_add_f32_e32 v80, 0, v78
	v_add_f32_e32 v80, v79, v80
	v_add_f32_e32 v80, v76, v80
	v_add_f32_e32 v80, v77, v80
	v_add_f32_e32 v80, v74, v80
	v_add_f32_e32 v80, v75, v80
	v_add_f32_e32 v80, v72, v80
	v_add_f32_e32 v80, v73, v80
	v_add_f32_e32 v80, v64, v80
	v_add_f32_e32 v80, v65, v80
	v_add_f32_e32 v80, v66, v80
	v_add_f32_e32 v80, v67, v80
	v_add_f32_e32 v80, v68, v80
	v_add_f32_e32 v80, v69, v80
	v_add_f32_e32 v80, v70, v80
	v_add_f32_e32 v80, v71, v80
	v_add_f32_e32 v80, v103, v80
	v_add_f32_e32 v80, v104, v80
	v_add_f32_e32 v80, v105, v80
	v_add_f32_e32 v80, v106, v80
	v_cndmask_b32_e32 v92, v248, v95, vcc
	v_exp_f32_e32 v95, v166
	v_add_f32_e32 v80, v107, v80
	v_add_f32_e32 v80, v108, v80
	v_add_f32_e32 v80, v109, v80
	v_add_f32_e32 v80, v110, v80
	v_add_f32_e32 v80, v95, v80
	v_add_f32_e32 v80, v96, v80
	v_add_f32_e32 v80, v97, v80
	v_add_f32_e32 v80, v98, v80
	v_add_f32_e32 v80, v99, v80
	v_add_f32_e32 v80, v100, v80
	v_add_f32_e32 v80, v101, v80
	v_add_f32_e32 v226, v102, v80
	v_mov_b32_e32 v227, v226
	v_cvt_pk_bf16_f32 v78, v78, v79
	v_cvt_pk_bf16_f32 v79, v76, v77
	v_cvt_pk_bf16_f32 v80, v74, v75
	v_cvt_pk_bf16_f32 v81, v72, v73
	v_cvt_pk_bf16_f32 v64, v64, v65
	v_cvt_pk_bf16_f32 v65, v66, v67
	v_cvt_pk_bf16_f32 v66, v68, v69
	s_nop 1
	v_permlane32_swap_b32_e32 v226, v227
	v_cvt_pk_bf16_f32 v67, v70, v71
	v_permlane32_swap_b32_e32 v64, v66
	v_cvt_pk_bf16_f32 v68, v103, v104
	v_cvt_pk_bf16_f32 v69, v105, v106
	v_cvt_pk_bf16_f32 v70, v107, v108
	v_cvt_pk_bf16_f32 v71, v109, v110
	v_cvt_pk_bf16_f32 v72, v95, v96
	v_cvt_pk_bf16_f32 v73, v97, v98
	v_cvt_pk_bf16_f32 v74, v99, v100
	v_cvt_pk_bf16_f32 v75, v101, v102
	v_permlane32_swap_b32_e32 v78, v80
	v_permlane32_swap_b32_e32 v79, v81
	v_permlane32_swap_b32_e32 v65, v67
	v_permlane32_swap_b32_e32 v68, v70
	v_permlane32_swap_b32_e32 v69, v71
	v_permlane32_swap_b32_e32 v72, v74
	v_permlane32_swap_b32_e32 v73, v75
	v_lshl_add_u64 v[76:77], v[178:179], 0, s[14:15]
	v_add_co_u32_e32 v96, vcc, s67, v76
	v_lshl_add_u64 v[108:109], v[180:181], 0, s[14:15]
	s_nop 0
	v_addc_co_u32_e32 v97, vcc, 0, v77, vcc
	v_add_co_u32_e32 v100, vcc, s67, v108
	global_load_dwordx4 v[96:99], v[96:97], off
	s_nop 0
	v_addc_co_u32_e32 v101, vcc, 0, v109, vcc
	v_add_co_u32_e32 v76, vcc, s60, v76
	global_load_dwordx4 v[100:103], v[100:101], off
	s_nop 0
	v_addc_co_u32_e32 v77, vcc, 0, v77, vcc
	global_load_dwordx4 v[104:107], v[76:77], off offset:2048
	v_add_co_u32_e32 v76, vcc, s60, v108
	s_nop 1
	v_addc_co_u32_e32 v77, vcc, 0, v109, vcc
	global_load_dwordx4 v[108:111], v[76:77], off offset:2048
	ds_read_b64_tr_b16 v[160:161], v193 offset:0
	ds_read_b64_tr_b16 v[162:163], v193 offset:0x800
	ds_read_b64_tr_b16 v[164:165], v193 offset:0x1000
	ds_read_b64_tr_b16 v[166:167], v193 offset:0x1800
	ds_read_b64_tr_b16 v[168:169], v193 offset:0x2000
	ds_read_b64_tr_b16 v[170:171], v193 offset:0x2800
	ds_read_b64_tr_b16 v[172:173], v193 offset:0x3000
	ds_read_b64_tr_b16 v[174:175], v193 offset:0x3800
	s_waitcnt lgkmcnt(0)
	s_nop 0
	v_mfma_f32_32x32x16_bf16 v[48:63], v[78:81], v[160:163], v[48:63]
	ds_read_b64_tr_b16 v[160:161], v193 offset:0x200
	ds_read_b64_tr_b16 v[162:163], v193 offset:0xa00
	v_mfma_f32_32x32x16_bf16 v[48:63], v[64:67], v[164:167], v[48:63]
	ds_read_b64_tr_b16 v[164:165], v193 offset:0x1200
	ds_read_b64_tr_b16 v[166:167], v193 offset:0x1a00
	v_mfma_f32_32x32x16_bf16 v[48:63], v[68:71], v[168:171], v[48:63]
	ds_read_b64_tr_b16 v[168:169], v193 offset:0x2200
	ds_read_b64_tr_b16 v[170:171], v193 offset:0x2a00
	v_mfma_f32_32x32x16_bf16 v[48:63], v[72:75], v[172:175], v[48:63]
	ds_read_b64_tr_b16 v[172:173], v193 offset:0x3200
	ds_read_b64_tr_b16 v[174:175], v193 offset:0x3a00
	s_waitcnt lgkmcnt(0)
	v_mfma_f32_32x32x16_bf16 v[32:47], v[78:81], v[160:163], v[32:47]
	ds_read_b64_tr_b16 v[160:161], v193 offset:0x400
	ds_read_b64_tr_b16 v[162:163], v193 offset:0xc00
	v_mfma_f32_32x32x16_bf16 v[32:47], v[64:67], v[164:167], v[32:47]
	ds_read_b64_tr_b16 v[164:165], v193 offset:0x1400
	ds_read_b64_tr_b16 v[166:167], v193 offset:0x1c00
	v_mfma_f32_32x32x16_bf16 v[32:47], v[68:71], v[168:171], v[32:47]
	ds_read_b64_tr_b16 v[168:169], v193 offset:0x2400
	ds_read_b64_tr_b16 v[170:171], v193 offset:0x2c00
	v_mfma_f32_32x32x16_bf16 v[32:47], v[72:75], v[172:175], v[32:47]
	ds_read_b64_tr_b16 v[172:173], v193 offset:0x3400
	ds_read_b64_tr_b16 v[174:175], v193 offset:0x3c00
	s_waitcnt lgkmcnt(0)
	v_mfma_f32_32x32x16_bf16 v[16:31], v[78:81], v[160:163], v[16:31]
	ds_read_b64_tr_b16 v[160:161], v193 offset:0x600
	ds_read_b64_tr_b16 v[162:163], v193 offset:0xe00
	v_mfma_f32_32x32x16_bf16 v[16:31], v[64:67], v[164:167], v[16:31]
	ds_read_b64_tr_b16 v[164:165], v193 offset:0x1600
	ds_read_b64_tr_b16 v[166:167], v193 offset:0x1e00
	v_mfma_f32_32x32x16_bf16 v[16:31], v[68:71], v[168:171], v[16:31]
	ds_read_b64_tr_b16 v[168:169], v193 offset:0x2600
	ds_read_b64_tr_b16 v[170:171], v193 offset:0x2e00
	v_mfma_f32_32x32x16_bf16 v[16:31], v[72:75], v[172:175], v[16:31]
	ds_read_b64_tr_b16 v[172:173], v193 offset:0x3600
	ds_read_b64_tr_b16 v[174:175], v193 offset:0x3e00
	s_waitcnt lgkmcnt(0)
	v_mfma_f32_32x32x16_bf16 v[0:15], v[78:81], v[160:163], v[0:15]
	v_mov_b32_e32 v246, 1.0
	v_mfma_f32_32x32x16_bf16 v[0:15], v[64:67], v[164:167], v[0:15]
	v_max_f32_e32 v64, v230, v230
	v_max_f32_e32 v65, v229, v229
	v_max_f32_e32 v64, v65, v64
	v_max3_f32 v64, v64, v231, v232
	v_max3_f32 v64, v64, v233, v234
	v_max3_f32 v64, v64, v235, v236
	v_max3_f32 v64, v64, v238, v240
	v_max3_f32 v64, v64, v242, v243
	v_max3_f32 v64, v64, v244, v245
	v_mfma_f32_32x32x16_bf16 v[0:15], v[68:71], v[168:171], v[0:15]
	v_max3_f32 v64, v64, v93, v94
	v_max3_f32 v64, v64, v225, v228
	v_max3_f32 v64, v64, v82, v83
	v_max3_f32 v64, v64, v84, v85
	v_max3_f32 v64, v64, v86, v87
	v_max3_f32 v64, v64, v88, v89
	v_max3_f32 v64, v64, v237, v239
	v_max3_f32 v64, v64, v241, v90
	v_mfma_f32_32x32x16_bf16 v[0:15], v[72:75], v[172:175], v[0:15]
	v_max3_f32 v64, v64, v91, v92
	v_mov_b32_e32 v65, v64
	s_nop 1
	v_permlane32_swap_b32_e32 v64, v65
	v_max_f32_e32 v65, v65, v65
	v_max_f32_e32 v64, v64, v64
	v_max_f32_e32 v64, v64, v65
	v_sub_f32_e32 v65, v64, v187
	v_cmp_ge_f32_e32 vcc, s66, v65
	s_cmp_eq_u64 vcc, exec
	s_cbranch_scc0 .LBB0_446

; template <class CF> __device__ __forceinline__ void partialSM(f32x16& p0, f32x16& p1, float& m_reg, float& mn, float& alpha) {
;     ...
;   else { mn = fmaxf(m_reg, pmax); alpha = __builtin_amdgcn_exp2f((m_reg - mn) * C); m_reg = mn; }
;   float mnC = -mn * C;
; #pragma unroll
;   for (int r = 0; r < 16; ++r) p0[r] = fmaf(p0[r], C, mnC);
; #pragma unroll
;   for (int r = 0; r < 16; ++r) p1[r] = fmaf(p1[r], C, mnC);
; #pragma unroll
;   for (int r = 0; r < 16; ++r) p0[r] = __builtin_amdgcn_exp2f(p0[r]);
; }
; __device__ __forceinline__ void finishSM(f32x16& p0, f32x16& p1, float alpha, float& l_reg, bf16x8& pa0, bf16x8& pa1, bf16x8& pa2, bf16x8& pa3) {
; #pragma unroll
;   for (int r = 0; r < 16; ++r) p1[r] = __builtin_amdgcn_exp2f(p1[r]);
;   float ps = 0;
; #pragma unroll
;   for (int r = 0; r < 16; ++r) ps += p0[r];
; #pragma unroll
;   for (int r = 0; r < 16; ++r) ps += p1[r];
;   { auto rr = __builtin_amdgcn_permlane32_swap(__float_as_uint(ps), __float_as_uint(ps), false, false);
;     ps = __uint_as_float(rr[0]) + __uint_as_float(rr[1]); }
;   l_reg = l_reg * alpha + ps;
;     ...
;   ATT_PK4(p0, 0, pa0); ATT_PK4(p0, 8, pa1); ATT_PK4(p1, 0, pa2); ATT_PK4(p1, 8, pa3);
;     ...
; }
; template <class CF> __device__ __forceinline__ void qkt(f32x16& p0, f32x16& p1, const char* Ks, const bf16x8* qr, const char* qx, int r32, int hi) {
;   p0 = f32x16{}; p1 = f32x16{};
; #pragma unroll
;   for (int d0 = 0; d0 < CF::ND0; ++d0) { const int cb = (d0 * 16 + hi * 8) * 2;
;     bf16x8 b0 = *reinterpret_cast<const bf16x8*>(Ks + (r32) * CF::KPITCH + (cb ^ ((r32 & CF::KSWM) << 4)));
;     bf16x8 b1 = *reinterpret_cast<const bf16x8*>(Ks + (32 + r32) * CF::KPITCH + (cb ^ ((r32 & CF::KSWM) << 4)));
;     bf16x8 q; if (d0 < CF::NQR) q = qr[d0 < CF::NQR ? d0 : 0]; else q = *reinterpret_cast<const bf16x8*>(qx + (d0 - CF::NQR) * 1024);
;     p0 = __builtin_amdgcn_mfma_f32_32x32x16_bf16(b0, q, p0, 0, 0, 0);
;     p1 = __builtin_amdgcn_mfma_f32_32x32x16_bf16(b1, q, p1, 0, 0, 0); }
; }
.LBB0_438:
	v_mul_f32_e32 v247, 0xbe0293ee, v187
	v_fmamk_f32 v64, v229, 0x3e0293ee, v247
	v_fmamk_f32 v65, v230, 0x3e0293ee, v247
	v_fmamk_f32 v66, v231, 0x3e0293ee, v247
	v_fmamk_f32 v67, v232, 0x3e0293ee, v247
	v_fmamk_f32 v68, v233, 0x3e0293ee, v247
	v_fmamk_f32 v69, v234, 0x3e0293ee, v247
	v_fmamk_f32 v70, v235, 0x3e0293ee, v247
	v_fmamk_f32 v71, v236, 0x3e0293ee, v247
	v_fmamk_f32 v72, v238, 0x3e0293ee, v247
	v_fmamk_f32 v73, v240, 0x3e0293ee, v247
	v_fmamk_f32 v74, v242, 0x3e0293ee, v247
	v_fmamk_f32 v75, v243, 0x3e0293ee, v247
	v_fmamk_f32 v76, v244, 0x3e0293ee, v247
	v_fmamk_f32 v77, v245, 0x3e0293ee, v247
	v_fmamk_f32 v78, v93, 0x3e0293ee, v247
	v_fmamk_f32 v79, v94, 0x3e0293ee, v247
	v_exp_f32_e32 v160, v64
	v_exp_f32_e32 v175, v65
	v_exp_f32_e32 v161, v66
	v_exp_f32_e32 v174, v67
	v_exp_f32_e32 v162, v68
	v_exp_f32_e32 v173, v69
	v_exp_f32_e32 v163, v70
	v_exp_f32_e32 v172, v71
	v_exp_f32_e32 v164, v72
	v_exp_f32_e32 v171, v73
	v_exp_f32_e32 v165, v74
	v_exp_f32_e32 v170, v75
	v_exp_f32_e32 v166, v76
	v_exp_f32_e32 v169, v77
	v_exp_f32_e32 v167, v78
	v_exp_f32_e32 v168, v79
	v_fmamk_f32 v238, v228, 0x3e0293ee, v247
	v_fmamk_f32 v229, v85, 0x3e0293ee, v247
	v_fmamk_f32 v228, v241, 0x3e0293ee, v247
	v_fmamk_f32 v236, v225, 0x3e0293ee, v247
	v_fmamk_f32 v240, v82, 0x3e0293ee, v247
	v_fmamk_f32 v242, v83, 0x3e0293ee, v247
	v_fmamk_f32 v243, v84, 0x3e0293ee, v247
	v_fmamk_f32 v230, v86, 0x3e0293ee, v247
	v_fmamk_f32 v231, v87, 0x3e0293ee, v247
	v_fmamk_f32 v232, v88, 0x3e0293ee, v247
	v_fmamk_f32 v233, v89, 0x3e0293ee, v247
	v_fmamk_f32 v234, v237, 0x3e0293ee, v247
	v_fmamk_f32 v235, v239, 0x3e0293ee, v247
	v_fmamk_f32 v237, v90, 0x3e0293ee, v247
	v_fmamk_f32 v239, v91, 0x3e0293ee, v247
	v_fmac_f32_e32 v247, 0x3e0293ee, v92
	s_waitcnt lgkmcnt(0)
	s_barrier
	ds_read_b128 v[64:67], v195 offset:32768
	ds_read_b128 v[68:71], v195 offset:40960
	ds_read_b128 v[206:209], v197 offset:32768
	ds_read_b128 v[210:213], v197 offset:40960
	v_exp_f32_e32 v218, v232
	v_exp_f32_e32 v219, v233
	s_waitcnt lgkmcnt(3)
	v_mfma_f32_32x32x16_bf16 v[80:95], v[64:67], v[140:143], 0
	v_exp_f32_e32 v220, v234
	v_exp_f32_e32 v221, v235
	v_exp_f32_e32 v232, v239
	v_exp_f32_e32 v233, v247
	v_mov_b32_e32 v225, v224
	s_waitcnt lgkmcnt(2)
	v_mfma_f32_32x32x16_bf16 v[64:79], v[68:71], v[140:143], 0
	ds_read_b128 v[144:147], v196 offset:32768
	ds_read_b128 v[148:151], v196 offset:40960
	s_waitcnt lgkmcnt(2)
	v_mfma_f32_32x32x16_bf16 v[64:79], v[210:213], v[136:139], v[64:79]
	v_mfma_f32_32x32x16_bf16 v[80:95], v[206:209], v[136:139], v[80:95]
	ds_read_b128 v[206:209], v198 offset:32768
	ds_read_b128 v[210:213], v198 offset:40960
	s_waitcnt lgkmcnt(2)
	v_mfma_f32_32x32x16_bf16 v[64:79], v[148:151], v[132:135], v[64:79]
	v_mfma_f32_32x32x16_bf16 v[80:95], v[144:147], v[132:135], v[80:95]
	ds_read_b128 v[144:147], v199 offset:32768
	ds_read_b128 v[148:151], v199 offset:40960
	s_waitcnt lgkmcnt(2)
	v_mfma_f32_32x32x16_bf16 v[64:79], v[210:213], v[128:131], v[64:79]
	v_mfma_f32_32x32x16_bf16 v[80:95], v[206:209], v[128:131], v[80:95]
	ds_read_b128 v[206:209], v201 offset:32768
	ds_read_b128 v[210:213], v201 offset:40960
	s_waitcnt lgkmcnt(2)
	v_mfma_f32_32x32x16_bf16 v[64:79], v[148:151], v[124:127], v[64:79]
	v_mfma_f32_32x32x16_bf16 v[80:95], v[144:147], v[124:127], v[80:95]
	ds_read_b128 v[144:147], v202 offset:32768
	ds_read_b128 v[148:151], v202 offset:40960
	s_waitcnt lgkmcnt(2)
	v_mfma_f32_32x32x16_bf16 v[64:79], v[210:213], v[120:123], v[64:79]
	v_mfma_f32_32x32x16_bf16 v[80:95], v[206:209], v[120:123], v[80:95]
	ds_read_b128 v[206:209], v203 offset:32768
	ds_read_b128 v[210:213], v203 offset:40960
	s_waitcnt lgkmcnt(2)
	v_mfma_f32_32x32x16_bf16 v[64:79], v[148:151], v[116:119], v[64:79]
	v_mfma_f32_32x32x16_bf16 v[80:95], v[144:147], v[116:119], v[80:95]
	s_waitcnt lgkmcnt(0)
	v_mfma_f32_32x32x16_bf16 v[64:79], v[210:213], v[112:115], v[64:79]
	v_exp_f32_e32 v212, v230
	v_exp_f32_e32 v230, v228
	v_add_f32_e32 v228, 0, v160
	v_add_f32_e32 v228, v175, v228
	v_add_f32_e32 v228, v161, v228
	v_add_f32_e32 v228, v174, v228
	v_add_f32_e32 v228, v162, v228
	v_add_f32_e32 v228, v173, v228
	v_add_f32_e32 v228, v163, v228
	v_add_f32_e32 v228, v172, v228
	v_add_f32_e32 v228, v164, v228
	v_add_f32_e32 v228, v171, v228
	v_add_f32_e32 v228, v165, v228
	v_add_f32_e32 v228, v170, v228
	v_mfma_f32_32x32x16_bf16 v[80:95], v[206:209], v[112:115], v[80:95]
	v_exp_f32_e32 v206, v236
	v_add_f32_e32 v228, v166, v228
	v_exp_f32_e32 v207, v238
	v_add_f32_e32 v228, v169, v228
	v_exp_f32_e32 v208, v240
	v_add_f32_e32 v228, v167, v228
	v_exp_f32_e32 v209, v242
	v_add_f32_e32 v228, v168, v228
	v_exp_f32_e32 v210, v243
	v_add_f32_e32 v228, v206, v228
	v_exp_f32_e32 v211, v229
	v_add_f32_e32 v228, v207, v228
	v_add_f32_e32 v228, v208, v228
	v_exp_f32_e32 v213, v231
	v_add_f32_e32 v228, v209, v228
	v_add_f32_e32 v228, v210, v228
	v_add_f32_e32 v228, v211, v228
	v_add_f32_e32 v228, v212, v228
	v_add_f32_e32 v228, v213, v228
	v_add_f32_e32 v228, v218, v228
	v_exp_f32_e32 v231, v237
	v_add_f32_e32 v228, v219, v228
	v_add_f32_e32 v228, v220, v228
	v_add_f32_e32 v228, v221, v228
	v_add_f32_e32 v228, v230, v228
	v_add_f32_e32 v228, v231, v228
	v_add_f32_e32 v228, v232, v228
	v_add_f32_e32 v228, v233, v228
	v_mov_b32_e32 v229, v228
	v_cvt_pk_bf16_f32 v160, v160, v175
	v_cvt_pk_bf16_f32 v161, v161, v174
	v_cvt_pk_bf16_f32 v162, v162, v173
	v_cvt_pk_bf16_f32 v163, v163, v172
	v_cvt_pk_bf16_f32 v164, v164, v171
	v_cvt_pk_bf16_f32 v165, v165, v170
	v_cvt_pk_bf16_f32 v166, v166, v169
	v_cvt_pk_bf16_f32 v167, v167, v168
	v_cvt_pk_bf16_f32 v168, v206, v207
	v_cvt_pk_bf16_f32 v169, v208, v209
	v_cvt_pk_bf16_f32 v170, v210, v211
	v_cvt_pk_bf16_f32 v171, v212, v213
	v_cvt_pk_bf16_f32 v172, v218, v219
	v_cvt_pk_bf16_f32 v173, v220, v221
	v_cvt_pk_bf16_f32 v174, v230, v231
	v_cvt_pk_bf16_f32 v175, v232, v233
	s_nop 1
	v_permlane32_swap_b32_e32 v228, v229
	v_permlane32_swap_b32_e32 v160, v162
	v_permlane32_swap_b32_e32 v161, v163
	v_permlane32_swap_b32_e32 v164, v166
	v_permlane32_swap_b32_e32 v165, v167
	v_permlane32_swap_b32_e32 v168, v170
	v_permlane32_swap_b32_e32 v169, v171
	v_permlane32_swap_b32_e32 v172, v174
	v_permlane32_swap_b32_e32 v173, v175
	s_cmp_ge_u32 s10, s0
	s_cselect_b64 s[18:19], -1, 0
	s_and_b64 vcc, exec, s[18:19]
	s_cbranch_vccnz .LBB0_440
	v_lshl_add_u64 v[152:153], v[182:183], 0, s[14:15]
	v_add_co_u32_e32 v144, vcc, 0x2a803000, v152
	v_lshl_add_u64 v[156:157], v[184:185], 0, s[14:15]
	s_nop 0
	v_addc_co_u32_e32 v145, vcc, 0, v153, vcc
	v_add_co_u32_e32 v148, vcc, 0x2a803000, v156
	global_load_dwordx4 v[144:147], v[144:145], off
	s_nop 0
	v_addc_co_u32_e32 v149, vcc, 0, v157, vcc
	v_add_co_u32_e32 v152, vcc, 0x2a801000, v152
	global_load_dwordx4 v[148:151], v[148:149], off
	s_nop 0
	v_addc_co_u32_e32 v153, vcc, 0, v153, vcc
	v_add_co_u32_e32 v156, vcc, 0x2a801000, v156
	global_load_dwordx4 v[152:155], v[152:153], off offset:2048
	s_nop 0
	v_addc_co_u32_e32 v157, vcc, 0, v157, vcc
	global_load_dwordx4 v[156:159], v[156:157], off offset:2048
